# P5 residual epilogue hand-rewritten: lane-pair permutation so each load/store covers full 128B rows, prefetch 2 row-groups ahead; plus static prio
# speedup vs baseline: 1.0004x; 1.0004x over previous
.LBB0_1016:
	v_and_b32_e32 v181, 8, v219
	v_cmp_ne_u32_e64 s[90:91], 0, v181
	v_sub_u32_e32 v191, v1, v181
	v_lshlrev_b32_e32 v181, 1, v181
	s_lshl_b32 s94, s0, 8
	v_add3_u32 v192, v179, v181, s94
	v_sub_u32_e32 v193, v179, v181
	v_add3_u32 v193, v193, 16, s94
	v_lshlrev_b32_e32 v182, 14, v191
	v_lshl_add_u32 v183, v193, 2, v182
	v_add_u32_e32 v183, 0x20000, v183
	v_lshl_add_u32 v182, v192, 2, v182
	v_lshlrev_b32_e32 v184, 13, v191
	v_lshl_add_u32 v185, v193, 1, v184
	v_add_u32_e32 v185, 0x10000, v185
	v_lshl_add_u32 v184, v192, 1, v184
	v_lshlrev_b32_e32 v186, 2, v192
	v_lshlrev_b32_e32 v187, 2, v193
	global_load_dwordx4 v[148:151], v186, s[44:45]
	global_load_dwordx4 v[156:159], v187, s[44:45]
	global_load_dwordx4 v[152:155], v186, s[44:45] offset:512
	global_load_dwordx4 v[160:163], v187, s[44:45] offset:512
	s_lshl_b32 s94, s0, 4
	s_lshl_b32 s95, s64, 2
	s_add_i32 s94, s94, s95
	v_lshlrev_b32_e32 v188, 8, v1
	v_add_u32_e32 v188, s94, v188
	v_xor_b32_e32 v189, 16, v219
	v_lshlrev_b32_e32 v189, 2, v189
	v_xor_b32_e32 v190, 32, v219
	v_lshlrev_b32_e32 v190, 2, v190
	s_lshl_b32 s94, s1, 8
	s_lshl_b32 s94, s94, 14
	s_add_u32 s84, s16, s94
	s_addc_u32 s85, s17, 0
	global_load_dwordx4 v[48:51], v182, s[84:85]
	global_load_dwordx4 v[56:59], v183, s[84:85]
	global_load_dwordx4 v[60:63], v182, s[84:85] offset:512
	global_load_dwordx4 v[64:67], v183, s[84:85] offset:512
	s_lshl_b32 s94, s1, 8
	s_add_i32 s94, s94, 16
	s_lshl_b32 s94, s94, 14
	s_add_u32 s84, s16, s94
	s_addc_u32 s85, s17, 0
	global_load_dwordx4 v[170:173], v182, s[84:85]
	global_load_dwordx4 v[174:177], v183, s[84:85]
	global_load_dwordx4 v[206:209], v182, s[84:85] offset:512
	global_load_dwordx4 v[232:235], v183, s[84:85] offset:512
	v_mov_b32_dpp v224, v140 row_ror:8 row_mask:0xf bank_mask:0xf
	v_mov_b32_dpp v225, v141 row_ror:8 row_mask:0xf bank_mask:0xf
	v_mov_b32_dpp v226, v142 row_ror:8 row_mask:0xf bank_mask:0xf
	v_mov_b32_dpp v227, v143 row_ror:8 row_mask:0xf bank_mask:0xf
	v_cndmask_b32_e64 v140, v224, v144, s[90:91]
	v_cndmask_b32_e64 v141, v225, v145, s[90:91]
	v_cndmask_b32_e64 v142, v226, v146, s[90:91]
	v_cndmask_b32_e64 v143, v227, v147, s[90:91]
	v_cndmask_b32_e64 v144, v144, v224, s[90:91]
	v_cndmask_b32_e64 v145, v145, v225, s[90:91]
	v_cndmask_b32_e64 v146, v146, v226, s[90:91]
	v_cndmask_b32_e64 v147, v147, v227, s[90:91]
	v_mov_b32_dpp v224, v132 row_ror:8 row_mask:0xf bank_mask:0xf
	v_mov_b32_dpp v225, v133 row_ror:8 row_mask:0xf bank_mask:0xf
	v_mov_b32_dpp v226, v134 row_ror:8 row_mask:0xf bank_mask:0xf
	v_mov_b32_dpp v227, v135 row_ror:8 row_mask:0xf bank_mask:0xf
	v_cndmask_b32_e64 v132, v224, v136, s[90:91]
	v_cndmask_b32_e64 v133, v225, v137, s[90:91]
	v_cndmask_b32_e64 v134, v226, v138, s[90:91]
	v_cndmask_b32_e64 v135, v227, v139, s[90:91]
	v_cndmask_b32_e64 v136, v136, v224, s[90:91]
	v_cndmask_b32_e64 v137, v137, v225, s[90:91]
	v_cndmask_b32_e64 v138, v138, v226, s[90:91]
	v_cndmask_b32_e64 v139, v139, v227, s[90:91]
	s_lshl_b32 s94, s1, 8
	s_lshl_b32 s94, s94, 14
	s_add_u32 s86, s48, s94
	s_addc_u32 s87, s49, 0
	s_lshl_b32 s94, s1, 8
	s_lshl_b32 s94, s94, 13
	s_add_u32 s88, s12, s94
	s_addc_u32 s89, s13, 0
	s_lshl_b32 s94, s1, 8
	s_lshl_b32 s94, s94, 8
	s_add_u32 s92, s46, s94
	s_addc_u32 s93, s47, 0
	s_waitcnt vmcnt(4)
	v_pk_add_f32 v[144:145], v[144:145], v[48:49]
	v_pk_add_f32 v[146:147], v[146:147], v[50:51]
	v_pk_add_f32 v[140:141], v[140:141], v[56:57]
	v_pk_add_f32 v[142:143], v[142:143], v[58:59]
	global_store_dwordx4 v182, v[144:147], s[86:87]
	global_store_dwordx4 v183, v[140:143], s[86:87]
	v_mul_f32_e32 v191, v144, v144
	v_fmac_f32_e32 v191, v145, v145
	v_fmac_f32_e32 v191, v146, v146
	v_fmac_f32_e32 v191, v147, v147
	v_mul_f32_e32 v192, v140, v140
	v_fmac_f32_e32 v192, v141, v141
	v_fmac_f32_e32 v192, v142, v142
	v_fmac_f32_e32 v192, v143, v143
	v_pk_mul_f32 v[224:225], v[144:145], v[148:149]
	v_pk_mul_f32 v[226:227], v[146:147], v[150:151]
	v_cvt_pk_bf16_f32 v210, v224, v225
	v_cvt_pk_bf16_f32 v211, v226, v227
	global_store_dwordx2 v184, v[210:211], s[88:89]
	v_pk_mul_f32 v[224:225], v[140:141], v[156:157]
	v_pk_mul_f32 v[226:227], v[142:143], v[158:159]
	v_cvt_pk_bf16_f32 v212, v224, v225
	v_cvt_pk_bf16_f32 v213, v226, v227
	global_store_dwordx2 v185, v[212:213], s[88:89]
	v_pk_add_f32 v[136:137], v[136:137], v[60:61]
	v_pk_add_f32 v[138:139], v[138:139], v[62:63]
	v_pk_add_f32 v[132:133], v[132:133], v[64:65]
	v_pk_add_f32 v[134:135], v[134:135], v[66:67]
	global_store_dwordx4 v182, v[136:139], s[86:87] offset:512
	global_store_dwordx4 v183, v[132:135], s[86:87] offset:512
	v_fmac_f32_e32 v191, v136, v136
	v_fmac_f32_e32 v191, v137, v137
	v_fmac_f32_e32 v191, v138, v138
	v_fmac_f32_e32 v191, v139, v139
	v_fmac_f32_e32 v192, v132, v132
	v_fmac_f32_e32 v192, v133, v133
	v_fmac_f32_e32 v192, v134, v134
	v_fmac_f32_e32 v192, v135, v135
	v_pk_mul_f32 v[224:225], v[136:137], v[152:153]
	v_pk_mul_f32 v[226:227], v[138:139], v[154:155]
	v_cvt_pk_bf16_f32 v210, v224, v225
	v_cvt_pk_bf16_f32 v211, v226, v227
	global_store_dwordx2 v184, v[210:211], s[88:89] offset:256
	v_pk_mul_f32 v[224:225], v[132:133], v[160:161]
	v_pk_mul_f32 v[226:227], v[134:135], v[162:163]
	v_cvt_pk_bf16_f32 v212, v224, v225
	v_cvt_pk_bf16_f32 v213, v226, v227
	global_store_dwordx2 v185, v[212:213], s[88:89] offset:256
	s_nop 1
	v_add_f32_dpp v193, v191, v191 row_ror:8 row_mask:0xf bank_mask:0xf
	v_add_f32_dpp v181, v192, v192 row_ror:8 row_mask:0xf bank_mask:0xf
	v_cndmask_b32_e64 v191, v193, v181, s[90:91]
	ds_bpermute_b32 v192, v189, v191
	s_waitcnt lgkmcnt(0)
	v_add_f32_e32 v191, v191, v192
	ds_bpermute_b32 v192, v190, v191
	s_waitcnt lgkmcnt(0)
	v_add_f32_e32 v191, v191, v192
	s_and_saveexec_b64 s[14:15], s[40:41]
	global_store_dword v188, v191, s[92:93]
	s_or_b64 exec, exec, s[14:15]
	s_lshl_b32 s94, s1, 8
	s_add_i32 s94, s94, 32
	s_lshl_b32 s94, s94, 14
	s_add_u32 s84, s16, s94
	s_addc_u32 s85, s17, 0
	global_load_dwordx4 v[144:147], v182, s[84:85]
	global_load_dwordx4 v[140:143], v183, s[84:85]
	global_load_dwordx4 v[136:139], v182, s[84:85] offset:512
	global_load_dwordx4 v[132:135], v183, s[84:85] offset:512
	v_mov_b32_dpp v224, v124 row_ror:8 row_mask:0xf bank_mask:0xf
	v_mov_b32_dpp v225, v125 row_ror:8 row_mask:0xf bank_mask:0xf
	v_mov_b32_dpp v226, v126 row_ror:8 row_mask:0xf bank_mask:0xf
	v_mov_b32_dpp v227, v127 row_ror:8 row_mask:0xf bank_mask:0xf
	v_cndmask_b32_e64 v124, v224, v128, s[90:91]
	v_cndmask_b32_e64 v125, v225, v129, s[90:91]
	v_cndmask_b32_e64 v126, v226, v130, s[90:91]
	v_cndmask_b32_e64 v127, v227, v131, s[90:91]
	v_cndmask_b32_e64 v128, v128, v224, s[90:91]
	v_cndmask_b32_e64 v129, v129, v225, s[90:91]
	v_cndmask_b32_e64 v130, v130, v226, s[90:91]
	v_cndmask_b32_e64 v131, v131, v227, s[90:91]
	v_mov_b32_dpp v224, v116 row_ror:8 row_mask:0xf bank_mask:0xf
	v_mov_b32_dpp v225, v117 row_ror:8 row_mask:0xf bank_mask:0xf
	v_mov_b32_dpp v226, v118 row_ror:8 row_mask:0xf bank_mask:0xf
	v_mov_b32_dpp v227, v119 row_ror:8 row_mask:0xf bank_mask:0xf
	v_cndmask_b32_e64 v116, v224, v120, s[90:91]
	v_cndmask_b32_e64 v117, v225, v121, s[90:91]
	v_cndmask_b32_e64 v118, v226, v122, s[90:91]
	v_cndmask_b32_e64 v119, v227, v123, s[90:91]
	v_cndmask_b32_e64 v120, v120, v224, s[90:91]
	v_cndmask_b32_e64 v121, v121, v225, s[90:91]
	v_cndmask_b32_e64 v122, v122, v226, s[90:91]
	v_cndmask_b32_e64 v123, v123, v227, s[90:91]
	s_lshl_b32 s94, s1, 8
	s_add_i32 s94, s94, 16
	s_lshl_b32 s94, s94, 14
	s_add_u32 s86, s48, s94
	s_addc_u32 s87, s49, 0
	s_lshl_b32 s94, s1, 8
	s_add_i32 s94, s94, 16
	s_lshl_b32 s94, s94, 13
	s_add_u32 s88, s12, s94
	s_addc_u32 s89, s13, 0
	s_lshl_b32 s94, s1, 8
	s_add_i32 s94, s94, 16
	s_lshl_b32 s94, s94, 8
	s_add_u32 s92, s46, s94
	s_addc_u32 s93, s47, 0
	s_waitcnt vmcnt(13)
	v_pk_add_f32 v[128:129], v[128:129], v[170:171]
	v_pk_add_f32 v[130:131], v[130:131], v[172:173]
	v_pk_add_f32 v[124:125], v[124:125], v[174:175]
	v_pk_add_f32 v[126:127], v[126:127], v[176:177]
	global_store_dwordx4 v182, v[128:131], s[86:87]
	global_store_dwordx4 v183, v[124:127], s[86:87]
	v_mul_f32_e32 v191, v128, v128
	v_fmac_f32_e32 v191, v129, v129
	v_fmac_f32_e32 v191, v130, v130
	v_fmac_f32_e32 v191, v131, v131
	v_mul_f32_e32 v192, v124, v124
	v_fmac_f32_e32 v192, v125, v125
	v_fmac_f32_e32 v192, v126, v126
	v_fmac_f32_e32 v192, v127, v127
	v_pk_mul_f32 v[224:225], v[128:129], v[148:149]
	v_pk_mul_f32 v[226:227], v[130:131], v[150:151]
	v_cvt_pk_bf16_f32 v210, v224, v225
	v_cvt_pk_bf16_f32 v211, v226, v227
	global_store_dwordx2 v184, v[210:211], s[88:89]
	v_pk_mul_f32 v[224:225], v[124:125], v[156:157]
	v_pk_mul_f32 v[226:227], v[126:127], v[158:159]
	v_cvt_pk_bf16_f32 v212, v224, v225
	v_cvt_pk_bf16_f32 v213, v226, v227
	global_store_dwordx2 v185, v[212:213], s[88:89]
	v_pk_add_f32 v[120:121], v[120:121], v[206:207]
	v_pk_add_f32 v[122:123], v[122:123], v[208:209]
	v_pk_add_f32 v[116:117], v[116:117], v[232:233]
	v_pk_add_f32 v[118:119], v[118:119], v[234:235]
	global_store_dwordx4 v182, v[120:123], s[86:87] offset:512
	global_store_dwordx4 v183, v[116:119], s[86:87] offset:512
	v_fmac_f32_e32 v191, v120, v120
	v_fmac_f32_e32 v191, v121, v121
	v_fmac_f32_e32 v191, v122, v122
	v_fmac_f32_e32 v191, v123, v123
	v_fmac_f32_e32 v192, v116, v116
	v_fmac_f32_e32 v192, v117, v117
	v_fmac_f32_e32 v192, v118, v118
	v_fmac_f32_e32 v192, v119, v119
	v_pk_mul_f32 v[224:225], v[120:121], v[152:153]
	v_pk_mul_f32 v[226:227], v[122:123], v[154:155]
	v_cvt_pk_bf16_f32 v210, v224, v225
	v_cvt_pk_bf16_f32 v211, v226, v227
	global_store_dwordx2 v184, v[210:211], s[88:89] offset:256
	v_pk_mul_f32 v[224:225], v[116:117], v[160:161]
	v_pk_mul_f32 v[226:227], v[118:119], v[162:163]
	v_cvt_pk_bf16_f32 v212, v224, v225
	v_cvt_pk_bf16_f32 v213, v226, v227
	global_store_dwordx2 v185, v[212:213], s[88:89] offset:256
	s_nop 1
	v_add_f32_dpp v193, v191, v191 row_ror:8 row_mask:0xf bank_mask:0xf
	v_add_f32_dpp v181, v192, v192 row_ror:8 row_mask:0xf bank_mask:0xf
	v_cndmask_b32_e64 v191, v193, v181, s[90:91]
	ds_bpermute_b32 v192, v189, v191
	s_waitcnt lgkmcnt(0)
	v_add_f32_e32 v191, v191, v192
	ds_bpermute_b32 v192, v190, v191
	s_waitcnt lgkmcnt(0)
	v_add_f32_e32 v191, v191, v192
	s_and_saveexec_b64 s[14:15], s[40:41]
	global_store_dword v188, v191, s[92:93]
	s_or_b64 exec, exec, s[14:15]
	s_lshl_b32 s94, s1, 8
	s_add_i32 s94, s94, 48
	s_lshl_b32 s94, s94, 14
	s_add_u32 s84, s16, s94
	s_addc_u32 s85, s17, 0
	global_load_dwordx4 v[128:131], v182, s[84:85]
	global_load_dwordx4 v[124:127], v183, s[84:85]
	global_load_dwordx4 v[120:123], v182, s[84:85] offset:512
	global_load_dwordx4 v[116:119], v183, s[84:85] offset:512
	v_mov_b32_dpp v224, v108 row_ror:8 row_mask:0xf bank_mask:0xf
	v_mov_b32_dpp v225, v109 row_ror:8 row_mask:0xf bank_mask:0xf
	v_mov_b32_dpp v226, v110 row_ror:8 row_mask:0xf bank_mask:0xf
	v_mov_b32_dpp v227, v111 row_ror:8 row_mask:0xf bank_mask:0xf
	v_cndmask_b32_e64 v108, v224, v112, s[90:91]
	v_cndmask_b32_e64 v109, v225, v113, s[90:91]
	v_cndmask_b32_e64 v110, v226, v114, s[90:91]
	v_cndmask_b32_e64 v111, v227, v115, s[90:91]
	v_cndmask_b32_e64 v112, v112, v224, s[90:91]
	v_cndmask_b32_e64 v113, v113, v225, s[90:91]
	v_cndmask_b32_e64 v114, v114, v226, s[90:91]
	v_cndmask_b32_e64 v115, v115, v227, s[90:91]
	v_mov_b32_dpp v224, v100 row_ror:8 row_mask:0xf bank_mask:0xf
	v_mov_b32_dpp v225, v101 row_ror:8 row_mask:0xf bank_mask:0xf
	v_mov_b32_dpp v226, v102 row_ror:8 row_mask:0xf bank_mask:0xf
	v_mov_b32_dpp v227, v103 row_ror:8 row_mask:0xf bank_mask:0xf
	v_cndmask_b32_e64 v100, v224, v104, s[90:91]
	v_cndmask_b32_e64 v101, v225, v105, s[90:91]
	v_cndmask_b32_e64 v102, v226, v106, s[90:91]
	v_cndmask_b32_e64 v103, v227, v107, s[90:91]
	v_cndmask_b32_e64 v104, v104, v224, s[90:91]
	v_cndmask_b32_e64 v105, v105, v225, s[90:91]
	v_cndmask_b32_e64 v106, v106, v226, s[90:91]
	v_cndmask_b32_e64 v107, v107, v227, s[90:91]
	s_lshl_b32 s94, s1, 8
	s_add_i32 s94, s94, 32
	s_lshl_b32 s94, s94, 14
	s_add_u32 s86, s48, s94
	s_addc_u32 s87, s49, 0
	s_lshl_b32 s94, s1, 8
	s_add_i32 s94, s94, 32
	s_lshl_b32 s94, s94, 13
	s_add_u32 s88, s12, s94
	s_addc_u32 s89, s13, 0
	s_lshl_b32 s94, s1, 8
	s_add_i32 s94, s94, 32
	s_lshl_b32 s94, s94, 8
	s_add_u32 s92, s46, s94
	s_addc_u32 s93, s47, 0
	s_waitcnt vmcnt(13)
	v_pk_add_f32 v[112:113], v[112:113], v[144:145]
	v_pk_add_f32 v[114:115], v[114:115], v[146:147]
	v_pk_add_f32 v[108:109], v[108:109], v[140:141]
	v_pk_add_f32 v[110:111], v[110:111], v[142:143]
	global_store_dwordx4 v182, v[112:115], s[86:87]
	global_store_dwordx4 v183, v[108:111], s[86:87]
	v_mul_f32_e32 v191, v112, v112
	v_fmac_f32_e32 v191, v113, v113
	v_fmac_f32_e32 v191, v114, v114
	v_fmac_f32_e32 v191, v115, v115
	v_mul_f32_e32 v192, v108, v108
	v_fmac_f32_e32 v192, v109, v109
	v_fmac_f32_e32 v192, v110, v110
	v_fmac_f32_e32 v192, v111, v111
	v_pk_mul_f32 v[224:225], v[112:113], v[148:149]
	v_pk_mul_f32 v[226:227], v[114:115], v[150:151]
	v_cvt_pk_bf16_f32 v210, v224, v225
	v_cvt_pk_bf16_f32 v211, v226, v227
	global_store_dwordx2 v184, v[210:211], s[88:89]
	v_pk_mul_f32 v[224:225], v[108:109], v[156:157]
	v_pk_mul_f32 v[226:227], v[110:111], v[158:159]
	v_cvt_pk_bf16_f32 v212, v224, v225
	v_cvt_pk_bf16_f32 v213, v226, v227
	global_store_dwordx2 v185, v[212:213], s[88:89]
	v_pk_add_f32 v[104:105], v[104:105], v[136:137]
	v_pk_add_f32 v[106:107], v[106:107], v[138:139]
	v_pk_add_f32 v[100:101], v[100:101], v[132:133]
	v_pk_add_f32 v[102:103], v[102:103], v[134:135]
	global_store_dwordx4 v182, v[104:107], s[86:87] offset:512
	global_store_dwordx4 v183, v[100:103], s[86:87] offset:512
	v_fmac_f32_e32 v191, v104, v104
	v_fmac_f32_e32 v191, v105, v105
	v_fmac_f32_e32 v191, v106, v106
	v_fmac_f32_e32 v191, v107, v107
	v_fmac_f32_e32 v192, v100, v100
	v_fmac_f32_e32 v192, v101, v101
	v_fmac_f32_e32 v192, v102, v102
	v_fmac_f32_e32 v192, v103, v103
	v_pk_mul_f32 v[224:225], v[104:105], v[152:153]
	v_pk_mul_f32 v[226:227], v[106:107], v[154:155]
	v_cvt_pk_bf16_f32 v210, v224, v225
	v_cvt_pk_bf16_f32 v211, v226, v227
	global_store_dwordx2 v184, v[210:211], s[88:89] offset:256
	v_pk_mul_f32 v[224:225], v[100:101], v[160:161]
	v_pk_mul_f32 v[226:227], v[102:103], v[162:163]
	v_cvt_pk_bf16_f32 v212, v224, v225
	v_cvt_pk_bf16_f32 v213, v226, v227
	global_store_dwordx2 v185, v[212:213], s[88:89] offset:256
	s_nop 1
	v_add_f32_dpp v193, v191, v191 row_ror:8 row_mask:0xf bank_mask:0xf
	v_add_f32_dpp v181, v192, v192 row_ror:8 row_mask:0xf bank_mask:0xf
	v_cndmask_b32_e64 v191, v193, v181, s[90:91]
	ds_bpermute_b32 v192, v189, v191
	s_waitcnt lgkmcnt(0)
	v_add_f32_e32 v191, v191, v192
	ds_bpermute_b32 v192, v190, v191
	s_waitcnt lgkmcnt(0)
	v_add_f32_e32 v191, v191, v192
	s_and_saveexec_b64 s[14:15], s[40:41]
	global_store_dword v188, v191, s[92:93]
	s_or_b64 exec, exec, s[14:15]
	s_lshl_b32 s94, s1, 8
	s_add_i32 s94, s94, 128
	s_lshl_b32 s94, s94, 14
	s_add_u32 s84, s16, s94
	s_addc_u32 s85, s17, 0
	global_load_dwordx4 v[112:115], v182, s[84:85]
	global_load_dwordx4 v[108:111], v183, s[84:85]
	global_load_dwordx4 v[104:107], v182, s[84:85] offset:512
	global_load_dwordx4 v[100:103], v183, s[84:85] offset:512
	v_mov_b32_dpp v224, v92 row_ror:8 row_mask:0xf bank_mask:0xf
	v_mov_b32_dpp v225, v93 row_ror:8 row_mask:0xf bank_mask:0xf
	v_mov_b32_dpp v226, v94 row_ror:8 row_mask:0xf bank_mask:0xf
	v_mov_b32_dpp v227, v95 row_ror:8 row_mask:0xf bank_mask:0xf
	v_cndmask_b32_e64 v92, v224, v96, s[90:91]
	v_cndmask_b32_e64 v93, v225, v97, s[90:91]
	v_cndmask_b32_e64 v94, v226, v98, s[90:91]
	v_cndmask_b32_e64 v95, v227, v99, s[90:91]
	v_cndmask_b32_e64 v96, v96, v224, s[90:91]
	v_cndmask_b32_e64 v97, v97, v225, s[90:91]
	v_cndmask_b32_e64 v98, v98, v226, s[90:91]
	v_cndmask_b32_e64 v99, v99, v227, s[90:91]
	v_mov_b32_dpp v224, v84 row_ror:8 row_mask:0xf bank_mask:0xf
	v_mov_b32_dpp v225, v85 row_ror:8 row_mask:0xf bank_mask:0xf
	v_mov_b32_dpp v226, v86 row_ror:8 row_mask:0xf bank_mask:0xf
	v_mov_b32_dpp v227, v87 row_ror:8 row_mask:0xf bank_mask:0xf
	v_cndmask_b32_e64 v84, v224, v88, s[90:91]
	v_cndmask_b32_e64 v85, v225, v89, s[90:91]
	v_cndmask_b32_e64 v86, v226, v90, s[90:91]
	v_cndmask_b32_e64 v87, v227, v91, s[90:91]
	v_cndmask_b32_e64 v88, v88, v224, s[90:91]
	v_cndmask_b32_e64 v89, v89, v225, s[90:91]
	v_cndmask_b32_e64 v90, v90, v226, s[90:91]
	v_cndmask_b32_e64 v91, v91, v227, s[90:91]
	s_lshl_b32 s94, s1, 8
	s_add_i32 s94, s94, 48
	s_lshl_b32 s94, s94, 14
	s_add_u32 s86, s48, s94
	s_addc_u32 s87, s49, 0
	s_lshl_b32 s94, s1, 8
	s_add_i32 s94, s94, 48
	s_lshl_b32 s94, s94, 13
	s_add_u32 s88, s12, s94
	s_addc_u32 s89, s13, 0
	s_lshl_b32 s94, s1, 8
	s_add_i32 s94, s94, 48
	s_lshl_b32 s94, s94, 8
	s_add_u32 s92, s46, s94
	s_addc_u32 s93, s47, 0
	s_waitcnt vmcnt(13)
	v_pk_add_f32 v[96:97], v[96:97], v[128:129]
	v_pk_add_f32 v[98:99], v[98:99], v[130:131]
	v_pk_add_f32 v[92:93], v[92:93], v[124:125]
	v_pk_add_f32 v[94:95], v[94:95], v[126:127]
	global_store_dwordx4 v182, v[96:99], s[86:87]
	global_store_dwordx4 v183, v[92:95], s[86:87]
	v_mul_f32_e32 v191, v96, v96
	v_fmac_f32_e32 v191, v97, v97
	v_fmac_f32_e32 v191, v98, v98
	v_fmac_f32_e32 v191, v99, v99
	v_mul_f32_e32 v192, v92, v92
	v_fmac_f32_e32 v192, v93, v93
	v_fmac_f32_e32 v192, v94, v94
	v_fmac_f32_e32 v192, v95, v95
	v_pk_mul_f32 v[224:225], v[96:97], v[148:149]
	v_pk_mul_f32 v[226:227], v[98:99], v[150:151]
	v_cvt_pk_bf16_f32 v210, v224, v225
	v_cvt_pk_bf16_f32 v211, v226, v227
	global_store_dwordx2 v184, v[210:211], s[88:89]
	v_pk_mul_f32 v[224:225], v[92:93], v[156:157]
	v_pk_mul_f32 v[226:227], v[94:95], v[158:159]
	v_cvt_pk_bf16_f32 v212, v224, v225
	v_cvt_pk_bf16_f32 v213, v226, v227
	global_store_dwordx2 v185, v[212:213], s[88:89]
	v_pk_add_f32 v[88:89], v[88:89], v[120:121]
	v_pk_add_f32 v[90:91], v[90:91], v[122:123]
	v_pk_add_f32 v[84:85], v[84:85], v[116:117]
	v_pk_add_f32 v[86:87], v[86:87], v[118:119]
	global_store_dwordx4 v182, v[88:91], s[86:87] offset:512
	global_store_dwordx4 v183, v[84:87], s[86:87] offset:512
	v_fmac_f32_e32 v191, v88, v88
	v_fmac_f32_e32 v191, v89, v89
	v_fmac_f32_e32 v191, v90, v90
	v_fmac_f32_e32 v191, v91, v91
	v_fmac_f32_e32 v192, v84, v84
	v_fmac_f32_e32 v192, v85, v85
	v_fmac_f32_e32 v192, v86, v86
	v_fmac_f32_e32 v192, v87, v87
	v_pk_mul_f32 v[224:225], v[88:89], v[152:153]
	v_pk_mul_f32 v[226:227], v[90:91], v[154:155]
	v_cvt_pk_bf16_f32 v210, v224, v225
	v_cvt_pk_bf16_f32 v211, v226, v227
	global_store_dwordx2 v184, v[210:211], s[88:89] offset:256
	v_pk_mul_f32 v[224:225], v[84:85], v[160:161]
	v_pk_mul_f32 v[226:227], v[86:87], v[162:163]
	v_cvt_pk_bf16_f32 v212, v224, v225
	v_cvt_pk_bf16_f32 v213, v226, v227
	global_store_dwordx2 v185, v[212:213], s[88:89] offset:256
	s_nop 1
	v_add_f32_dpp v193, v191, v191 row_ror:8 row_mask:0xf bank_mask:0xf
	v_add_f32_dpp v181, v192, v192 row_ror:8 row_mask:0xf bank_mask:0xf
	v_cndmask_b32_e64 v191, v193, v181, s[90:91]
	ds_bpermute_b32 v192, v189, v191
	s_waitcnt lgkmcnt(0)
	v_add_f32_e32 v191, v191, v192
	ds_bpermute_b32 v192, v190, v191
	s_waitcnt lgkmcnt(0)
	v_add_f32_e32 v191, v191, v192
	s_and_saveexec_b64 s[14:15], s[40:41]
	global_store_dword v188, v191, s[92:93]
	s_or_b64 exec, exec, s[14:15]
	s_lshl_b32 s94, s1, 8
	s_add_i32 s94, s94, 144
	s_lshl_b32 s94, s94, 14
	s_add_u32 s84, s16, s94
	s_addc_u32 s85, s17, 0
	global_load_dwordx4 v[96:99], v182, s[84:85]
	global_load_dwordx4 v[92:95], v183, s[84:85]
	global_load_dwordx4 v[88:91], v182, s[84:85] offset:512
	global_load_dwordx4 v[84:87], v183, s[84:85] offset:512
	v_mov_b32_dpp v224, v76 row_ror:8 row_mask:0xf bank_mask:0xf
	v_mov_b32_dpp v225, v77 row_ror:8 row_mask:0xf bank_mask:0xf
	v_mov_b32_dpp v226, v78 row_ror:8 row_mask:0xf bank_mask:0xf
	v_mov_b32_dpp v227, v79 row_ror:8 row_mask:0xf bank_mask:0xf
	v_cndmask_b32_e64 v76, v224, v80, s[90:91]
	v_cndmask_b32_e64 v77, v225, v81, s[90:91]
	v_cndmask_b32_e64 v78, v226, v82, s[90:91]
	v_cndmask_b32_e64 v79, v227, v83, s[90:91]
	v_cndmask_b32_e64 v80, v80, v224, s[90:91]
	v_cndmask_b32_e64 v81, v81, v225, s[90:91]
	v_cndmask_b32_e64 v82, v82, v226, s[90:91]
	v_cndmask_b32_e64 v83, v83, v227, s[90:91]
	v_mov_b32_dpp v224, v68 row_ror:8 row_mask:0xf bank_mask:0xf
	v_mov_b32_dpp v225, v69 row_ror:8 row_mask:0xf bank_mask:0xf
	v_mov_b32_dpp v226, v70 row_ror:8 row_mask:0xf bank_mask:0xf
	v_mov_b32_dpp v227, v71 row_ror:8 row_mask:0xf bank_mask:0xf
	v_cndmask_b32_e64 v68, v224, v72, s[90:91]
	v_cndmask_b32_e64 v69, v225, v73, s[90:91]
	v_cndmask_b32_e64 v70, v226, v74, s[90:91]
	v_cndmask_b32_e64 v71, v227, v75, s[90:91]
	v_cndmask_b32_e64 v72, v72, v224, s[90:91]
	v_cndmask_b32_e64 v73, v73, v225, s[90:91]
	v_cndmask_b32_e64 v74, v74, v226, s[90:91]
	v_cndmask_b32_e64 v75, v75, v227, s[90:91]
	s_lshl_b32 s94, s1, 8
	s_add_i32 s94, s94, 128
	s_lshl_b32 s94, s94, 14
	s_add_u32 s86, s48, s94
	s_addc_u32 s87, s49, 0
	s_lshl_b32 s94, s1, 8
	s_add_i32 s94, s94, 128
	s_lshl_b32 s94, s94, 13
	s_add_u32 s88, s12, s94
	s_addc_u32 s89, s13, 0
	s_lshl_b32 s94, s1, 8
	s_add_i32 s94, s94, 128
	s_lshl_b32 s94, s94, 8
	s_add_u32 s92, s46, s94
	s_addc_u32 s93, s47, 0
	s_waitcnt vmcnt(13)
	v_pk_add_f32 v[80:81], v[80:81], v[112:113]
	v_pk_add_f32 v[82:83], v[82:83], v[114:115]
	v_pk_add_f32 v[76:77], v[76:77], v[108:109]
	v_pk_add_f32 v[78:79], v[78:79], v[110:111]
	global_store_dwordx4 v182, v[80:83], s[86:87]
	global_store_dwordx4 v183, v[76:79], s[86:87]
	v_mul_f32_e32 v191, v80, v80
	v_fmac_f32_e32 v191, v81, v81
	v_fmac_f32_e32 v191, v82, v82
	v_fmac_f32_e32 v191, v83, v83
	v_mul_f32_e32 v192, v76, v76
	v_fmac_f32_e32 v192, v77, v77
	v_fmac_f32_e32 v192, v78, v78
	v_fmac_f32_e32 v192, v79, v79
	v_pk_mul_f32 v[224:225], v[80:81], v[148:149]
	v_pk_mul_f32 v[226:227], v[82:83], v[150:151]
	v_cvt_pk_bf16_f32 v210, v224, v225
	v_cvt_pk_bf16_f32 v211, v226, v227
	global_store_dwordx2 v184, v[210:211], s[88:89]
	v_pk_mul_f32 v[224:225], v[76:77], v[156:157]
	v_pk_mul_f32 v[226:227], v[78:79], v[158:159]
	v_cvt_pk_bf16_f32 v212, v224, v225
	v_cvt_pk_bf16_f32 v213, v226, v227
	global_store_dwordx2 v185, v[212:213], s[88:89]
	v_pk_add_f32 v[72:73], v[72:73], v[104:105]
	v_pk_add_f32 v[74:75], v[74:75], v[106:107]
	v_pk_add_f32 v[68:69], v[68:69], v[100:101]
	v_pk_add_f32 v[70:71], v[70:71], v[102:103]
	global_store_dwordx4 v182, v[72:75], s[86:87] offset:512
	global_store_dwordx4 v183, v[68:71], s[86:87] offset:512
	v_fmac_f32_e32 v191, v72, v72
	v_fmac_f32_e32 v191, v73, v73
	v_fmac_f32_e32 v191, v74, v74
	v_fmac_f32_e32 v191, v75, v75
	v_fmac_f32_e32 v192, v68, v68
	v_fmac_f32_e32 v192, v69, v69
	v_fmac_f32_e32 v192, v70, v70
	v_fmac_f32_e32 v192, v71, v71
	v_pk_mul_f32 v[224:225], v[72:73], v[152:153]
	v_pk_mul_f32 v[226:227], v[74:75], v[154:155]
	v_cvt_pk_bf16_f32 v210, v224, v225
	v_cvt_pk_bf16_f32 v211, v226, v227
	global_store_dwordx2 v184, v[210:211], s[88:89] offset:256
	v_pk_mul_f32 v[224:225], v[68:69], v[160:161]
	v_pk_mul_f32 v[226:227], v[70:71], v[162:163]
	v_cvt_pk_bf16_f32 v212, v224, v225
	v_cvt_pk_bf16_f32 v213, v226, v227
	global_store_dwordx2 v185, v[212:213], s[88:89] offset:256
	s_nop 1
	v_add_f32_dpp v193, v191, v191 row_ror:8 row_mask:0xf bank_mask:0xf
	v_add_f32_dpp v181, v192, v192 row_ror:8 row_mask:0xf bank_mask:0xf
	v_cndmask_b32_e64 v191, v193, v181, s[90:91]
	ds_bpermute_b32 v192, v189, v191
	s_waitcnt lgkmcnt(0)
	v_add_f32_e32 v191, v191, v192
	ds_bpermute_b32 v192, v190, v191
	s_waitcnt lgkmcnt(0)
	v_add_f32_e32 v191, v191, v192
	s_and_saveexec_b64 s[14:15], s[40:41]
	global_store_dword v188, v191, s[92:93]
	s_or_b64 exec, exec, s[14:15]
	s_lshl_b32 s94, s1, 8
	s_add_i32 s94, s94, 160
	s_lshl_b32 s94, s94, 14
	s_add_u32 s84, s16, s94
	s_addc_u32 s85, s17, 0
	global_load_dwordx4 v[80:83], v182, s[84:85]
	global_load_dwordx4 v[76:79], v183, s[84:85]
	global_load_dwordx4 v[72:75], v182, s[84:85] offset:512
	global_load_dwordx4 v[68:71], v183, s[84:85] offset:512
	v_mov_b32_dpp v224, v44 row_ror:8 row_mask:0xf bank_mask:0xf
	v_mov_b32_dpp v225, v45 row_ror:8 row_mask:0xf bank_mask:0xf
	v_mov_b32_dpp v226, v46 row_ror:8 row_mask:0xf bank_mask:0xf
	v_mov_b32_dpp v227, v47 row_ror:8 row_mask:0xf bank_mask:0xf
	v_cndmask_b32_e64 v44, v224, v52, s[90:91]
	v_cndmask_b32_e64 v45, v225, v53, s[90:91]
	v_cndmask_b32_e64 v46, v226, v54, s[90:91]
	v_cndmask_b32_e64 v47, v227, v55, s[90:91]
	v_cndmask_b32_e64 v52, v52, v224, s[90:91]
	v_cndmask_b32_e64 v53, v53, v225, s[90:91]
	v_cndmask_b32_e64 v54, v54, v226, s[90:91]
	v_cndmask_b32_e64 v55, v55, v227, s[90:91]
	v_mov_b32_dpp v224, v36 row_ror:8 row_mask:0xf bank_mask:0xf
	v_mov_b32_dpp v225, v37 row_ror:8 row_mask:0xf bank_mask:0xf
	v_mov_b32_dpp v226, v38 row_ror:8 row_mask:0xf bank_mask:0xf
	v_mov_b32_dpp v227, v39 row_ror:8 row_mask:0xf bank_mask:0xf
	v_cndmask_b32_e64 v36, v224, v40, s[90:91]
	v_cndmask_b32_e64 v37, v225, v41, s[90:91]
	v_cndmask_b32_e64 v38, v226, v42, s[90:91]
	v_cndmask_b32_e64 v39, v227, v43, s[90:91]
	v_cndmask_b32_e64 v40, v40, v224, s[90:91]
	v_cndmask_b32_e64 v41, v41, v225, s[90:91]
	v_cndmask_b32_e64 v42, v42, v226, s[90:91]
	v_cndmask_b32_e64 v43, v43, v227, s[90:91]
	s_lshl_b32 s94, s1, 8
	s_add_i32 s94, s94, 144
	s_lshl_b32 s94, s94, 14
	s_add_u32 s86, s48, s94
	s_addc_u32 s87, s49, 0
	s_lshl_b32 s94, s1, 8
	s_add_i32 s94, s94, 144
	s_lshl_b32 s94, s94, 13
	s_add_u32 s88, s12, s94
	s_addc_u32 s89, s13, 0
	s_lshl_b32 s94, s1, 8
	s_add_i32 s94, s94, 144
	s_lshl_b32 s94, s94, 8
	s_add_u32 s92, s46, s94
	s_addc_u32 s93, s47, 0
	s_waitcnt vmcnt(13)
	v_pk_add_f32 v[52:53], v[52:53], v[96:97]
	v_pk_add_f32 v[54:55], v[54:55], v[98:99]
	v_pk_add_f32 v[44:45], v[44:45], v[92:93]
	v_pk_add_f32 v[46:47], v[46:47], v[94:95]
	global_store_dwordx4 v182, v[52:55], s[86:87]
	global_store_dwordx4 v183, v[44:47], s[86:87]
	v_mul_f32_e32 v191, v52, v52
	v_fmac_f32_e32 v191, v53, v53
	v_fmac_f32_e32 v191, v54, v54
	v_fmac_f32_e32 v191, v55, v55
	v_mul_f32_e32 v192, v44, v44
	v_fmac_f32_e32 v192, v45, v45
	v_fmac_f32_e32 v192, v46, v46
	v_fmac_f32_e32 v192, v47, v47
	v_pk_mul_f32 v[224:225], v[52:53], v[148:149]
	v_pk_mul_f32 v[226:227], v[54:55], v[150:151]
	v_cvt_pk_bf16_f32 v210, v224, v225
	v_cvt_pk_bf16_f32 v211, v226, v227
	global_store_dwordx2 v184, v[210:211], s[88:89]
	v_pk_mul_f32 v[224:225], v[44:45], v[156:157]
	v_pk_mul_f32 v[226:227], v[46:47], v[158:159]
	v_cvt_pk_bf16_f32 v212, v224, v225
	v_cvt_pk_bf16_f32 v213, v226, v227
	global_store_dwordx2 v185, v[212:213], s[88:89]
	v_pk_add_f32 v[40:41], v[40:41], v[88:89]
	v_pk_add_f32 v[42:43], v[42:43], v[90:91]
	v_pk_add_f32 v[36:37], v[36:37], v[84:85]
	v_pk_add_f32 v[38:39], v[38:39], v[86:87]
	global_store_dwordx4 v182, v[40:43], s[86:87] offset:512
	global_store_dwordx4 v183, v[36:39], s[86:87] offset:512
	v_fmac_f32_e32 v191, v40, v40
	v_fmac_f32_e32 v191, v41, v41
	v_fmac_f32_e32 v191, v42, v42
	v_fmac_f32_e32 v191, v43, v43
	v_fmac_f32_e32 v192, v36, v36
	v_fmac_f32_e32 v192, v37, v37
	v_fmac_f32_e32 v192, v38, v38
	v_fmac_f32_e32 v192, v39, v39
	v_pk_mul_f32 v[224:225], v[40:41], v[152:153]
	v_pk_mul_f32 v[226:227], v[42:43], v[154:155]
	v_cvt_pk_bf16_f32 v210, v224, v225
	v_cvt_pk_bf16_f32 v211, v226, v227
	global_store_dwordx2 v184, v[210:211], s[88:89] offset:256
	v_pk_mul_f32 v[224:225], v[36:37], v[160:161]
	v_pk_mul_f32 v[226:227], v[38:39], v[162:163]
	v_cvt_pk_bf16_f32 v212, v224, v225
	v_cvt_pk_bf16_f32 v213, v226, v227
	global_store_dwordx2 v185, v[212:213], s[88:89] offset:256
	s_nop 1
	v_add_f32_dpp v193, v191, v191 row_ror:8 row_mask:0xf bank_mask:0xf
	v_add_f32_dpp v181, v192, v192 row_ror:8 row_mask:0xf bank_mask:0xf
	v_cndmask_b32_e64 v191, v193, v181, s[90:91]
	ds_bpermute_b32 v192, v189, v191
	s_waitcnt lgkmcnt(0)
	v_add_f32_e32 v191, v191, v192
	ds_bpermute_b32 v192, v190, v191
	s_waitcnt lgkmcnt(0)
	v_add_f32_e32 v191, v191, v192
	s_and_saveexec_b64 s[14:15], s[40:41]
	global_store_dword v188, v191, s[92:93]
	s_or_b64 exec, exec, s[14:15]
	s_lshl_b32 s94, s1, 8
	s_add_i32 s94, s94, 176
	s_lshl_b32 s94, s94, 14
	s_add_u32 s84, s16, s94
	s_addc_u32 s85, s17, 0
	global_load_dwordx4 v[52:55], v182, s[84:85]
	global_load_dwordx4 v[44:47], v183, s[84:85]
	global_load_dwordx4 v[40:43], v182, s[84:85] offset:512
	global_load_dwordx4 v[36:39], v183, s[84:85] offset:512
	v_mov_b32_dpp v224, v28 row_ror:8 row_mask:0xf bank_mask:0xf
	v_mov_b32_dpp v225, v29 row_ror:8 row_mask:0xf bank_mask:0xf
	v_mov_b32_dpp v226, v30 row_ror:8 row_mask:0xf bank_mask:0xf
	v_mov_b32_dpp v227, v31 row_ror:8 row_mask:0xf bank_mask:0xf
	v_cndmask_b32_e64 v28, v224, v32, s[90:91]
	v_cndmask_b32_e64 v29, v225, v33, s[90:91]
	v_cndmask_b32_e64 v30, v226, v34, s[90:91]
	v_cndmask_b32_e64 v31, v227, v35, s[90:91]
	v_cndmask_b32_e64 v32, v32, v224, s[90:91]
	v_cndmask_b32_e64 v33, v33, v225, s[90:91]
	v_cndmask_b32_e64 v34, v34, v226, s[90:91]
	v_cndmask_b32_e64 v35, v35, v227, s[90:91]
	v_mov_b32_dpp v224, v20 row_ror:8 row_mask:0xf bank_mask:0xf
	v_mov_b32_dpp v225, v21 row_ror:8 row_mask:0xf bank_mask:0xf
	v_mov_b32_dpp v226, v22 row_ror:8 row_mask:0xf bank_mask:0xf
	v_mov_b32_dpp v227, v23 row_ror:8 row_mask:0xf bank_mask:0xf
	v_cndmask_b32_e64 v20, v224, v24, s[90:91]
	v_cndmask_b32_e64 v21, v225, v25, s[90:91]
	v_cndmask_b32_e64 v22, v226, v26, s[90:91]
	v_cndmask_b32_e64 v23, v227, v27, s[90:91]
	v_cndmask_b32_e64 v24, v24, v224, s[90:91]
	v_cndmask_b32_e64 v25, v25, v225, s[90:91]
	v_cndmask_b32_e64 v26, v26, v226, s[90:91]
	v_cndmask_b32_e64 v27, v27, v227, s[90:91]
	s_lshl_b32 s94, s1, 8
	s_add_i32 s94, s94, 160
	s_lshl_b32 s94, s94, 14
	s_add_u32 s86, s48, s94
	s_addc_u32 s87, s49, 0
	s_lshl_b32 s94, s1, 8
	s_add_i32 s94, s94, 160
	s_lshl_b32 s94, s94, 13
	s_add_u32 s88, s12, s94
	s_addc_u32 s89, s13, 0
	s_lshl_b32 s94, s1, 8
	s_add_i32 s94, s94, 160
	s_lshl_b32 s94, s94, 8
	s_add_u32 s92, s46, s94
	s_addc_u32 s93, s47, 0
	s_waitcnt vmcnt(13)
	v_pk_add_f32 v[32:33], v[32:33], v[80:81]
	v_pk_add_f32 v[34:35], v[34:35], v[82:83]
	v_pk_add_f32 v[28:29], v[28:29], v[76:77]
	v_pk_add_f32 v[30:31], v[30:31], v[78:79]
	global_store_dwordx4 v182, v[32:35], s[86:87]
	global_store_dwordx4 v183, v[28:31], s[86:87]
	v_mul_f32_e32 v191, v32, v32
	v_fmac_f32_e32 v191, v33, v33
	v_fmac_f32_e32 v191, v34, v34
	v_fmac_f32_e32 v191, v35, v35
	v_mul_f32_e32 v192, v28, v28
	v_fmac_f32_e32 v192, v29, v29
	v_fmac_f32_e32 v192, v30, v30
	v_fmac_f32_e32 v192, v31, v31
	v_pk_mul_f32 v[224:225], v[32:33], v[148:149]
	v_pk_mul_f32 v[226:227], v[34:35], v[150:151]
	v_cvt_pk_bf16_f32 v210, v224, v225
	v_cvt_pk_bf16_f32 v211, v226, v227
	global_store_dwordx2 v184, v[210:211], s[88:89]
	v_pk_mul_f32 v[224:225], v[28:29], v[156:157]
	v_pk_mul_f32 v[226:227], v[30:31], v[158:159]
	v_cvt_pk_bf16_f32 v212, v224, v225
	v_cvt_pk_bf16_f32 v213, v226, v227
	global_store_dwordx2 v185, v[212:213], s[88:89]
	v_pk_add_f32 v[24:25], v[24:25], v[72:73]
	v_pk_add_f32 v[26:27], v[26:27], v[74:75]
	v_pk_add_f32 v[20:21], v[20:21], v[68:69]
	v_pk_add_f32 v[22:23], v[22:23], v[70:71]
	global_store_dwordx4 v182, v[24:27], s[86:87] offset:512
	global_store_dwordx4 v183, v[20:23], s[86:87] offset:512
	v_fmac_f32_e32 v191, v24, v24
	v_fmac_f32_e32 v191, v25, v25
	v_fmac_f32_e32 v191, v26, v26
	v_fmac_f32_e32 v191, v27, v27
	v_fmac_f32_e32 v192, v20, v20
	v_fmac_f32_e32 v192, v21, v21
	v_fmac_f32_e32 v192, v22, v22
	v_fmac_f32_e32 v192, v23, v23
	v_pk_mul_f32 v[224:225], v[24:25], v[152:153]
	v_pk_mul_f32 v[226:227], v[26:27], v[154:155]
	v_cvt_pk_bf16_f32 v210, v224, v225
	v_cvt_pk_bf16_f32 v211, v226, v227
	global_store_dwordx2 v184, v[210:211], s[88:89] offset:256
	v_pk_mul_f32 v[224:225], v[20:21], v[160:161]
	v_pk_mul_f32 v[226:227], v[22:23], v[162:163]
	v_cvt_pk_bf16_f32 v212, v224, v225
	v_cvt_pk_bf16_f32 v213, v226, v227
	global_store_dwordx2 v185, v[212:213], s[88:89] offset:256
	s_nop 1
	v_add_f32_dpp v193, v191, v191 row_ror:8 row_mask:0xf bank_mask:0xf
	v_add_f32_dpp v181, v192, v192 row_ror:8 row_mask:0xf bank_mask:0xf
	v_cndmask_b32_e64 v191, v193, v181, s[90:91]
	ds_bpermute_b32 v192, v189, v191
	s_waitcnt lgkmcnt(0)
	v_add_f32_e32 v191, v191, v192
	ds_bpermute_b32 v192, v190, v191
	s_waitcnt lgkmcnt(0)
	v_add_f32_e32 v191, v191, v192
	s_and_saveexec_b64 s[14:15], s[40:41]
	global_store_dword v188, v191, s[92:93]
	s_or_b64 exec, exec, s[14:15]
	v_mov_b32_dpp v224, v12 row_ror:8 row_mask:0xf bank_mask:0xf
	v_mov_b32_dpp v225, v13 row_ror:8 row_mask:0xf bank_mask:0xf
	v_mov_b32_dpp v226, v14 row_ror:8 row_mask:0xf bank_mask:0xf
	v_mov_b32_dpp v227, v15 row_ror:8 row_mask:0xf bank_mask:0xf
	v_cndmask_b32_e64 v12, v224, v16, s[90:91]
	v_cndmask_b32_e64 v13, v225, v17, s[90:91]
	v_cndmask_b32_e64 v14, v226, v18, s[90:91]
	v_cndmask_b32_e64 v15, v227, v19, s[90:91]
	v_cndmask_b32_e64 v16, v16, v224, s[90:91]
	v_cndmask_b32_e64 v17, v17, v225, s[90:91]
	v_cndmask_b32_e64 v18, v18, v226, s[90:91]
	v_cndmask_b32_e64 v19, v19, v227, s[90:91]
	v_mov_b32_dpp v224, v4 row_ror:8 row_mask:0xf bank_mask:0xf
	v_mov_b32_dpp v225, v5 row_ror:8 row_mask:0xf bank_mask:0xf
	v_mov_b32_dpp v226, v6 row_ror:8 row_mask:0xf bank_mask:0xf
	v_mov_b32_dpp v227, v7 row_ror:8 row_mask:0xf bank_mask:0xf
	v_cndmask_b32_e64 v4, v224, v8, s[90:91]
	v_cndmask_b32_e64 v5, v225, v9, s[90:91]
	v_cndmask_b32_e64 v6, v226, v10, s[90:91]
	v_cndmask_b32_e64 v7, v227, v11, s[90:91]
	v_cndmask_b32_e64 v8, v8, v224, s[90:91]
	v_cndmask_b32_e64 v9, v9, v225, s[90:91]
	v_cndmask_b32_e64 v10, v10, v226, s[90:91]
	v_cndmask_b32_e64 v11, v11, v227, s[90:91]
	s_lshl_b32 s94, s1, 8
	s_add_i32 s94, s94, 176
	s_lshl_b32 s94, s94, 14
	s_add_u32 s86, s48, s94
	s_addc_u32 s87, s49, 0
	s_lshl_b32 s94, s1, 8
	s_add_i32 s94, s94, 176
	s_lshl_b32 s94, s94, 13
	s_add_u32 s88, s12, s94
	s_addc_u32 s89, s13, 0
	s_lshl_b32 s94, s1, 8
	s_add_i32 s94, s94, 176
	s_lshl_b32 s94, s94, 8
	s_add_u32 s92, s46, s94
	s_addc_u32 s93, s47, 0
	s_waitcnt vmcnt(9)
	v_pk_add_f32 v[16:17], v[16:17], v[52:53]
	v_pk_add_f32 v[18:19], v[18:19], v[54:55]
	v_pk_add_f32 v[12:13], v[12:13], v[44:45]
	v_pk_add_f32 v[14:15], v[14:15], v[46:47]
	global_store_dwordx4 v182, v[16:19], s[86:87]
	global_store_dwordx4 v183, v[12:15], s[86:87]
	v_mul_f32_e32 v191, v16, v16
	v_fmac_f32_e32 v191, v17, v17
	v_fmac_f32_e32 v191, v18, v18
	v_fmac_f32_e32 v191, v19, v19
	v_mul_f32_e32 v192, v12, v12
	v_fmac_f32_e32 v192, v13, v13
	v_fmac_f32_e32 v192, v14, v14
	v_fmac_f32_e32 v192, v15, v15
	v_pk_mul_f32 v[224:225], v[16:17], v[148:149]
	v_pk_mul_f32 v[226:227], v[18:19], v[150:151]
	v_cvt_pk_bf16_f32 v210, v224, v225
	v_cvt_pk_bf16_f32 v211, v226, v227
	global_store_dwordx2 v184, v[210:211], s[88:89]
	v_pk_mul_f32 v[224:225], v[12:13], v[156:157]
	v_pk_mul_f32 v[226:227], v[14:15], v[158:159]
	v_cvt_pk_bf16_f32 v212, v224, v225
	v_cvt_pk_bf16_f32 v213, v226, v227
	global_store_dwordx2 v185, v[212:213], s[88:89]
	v_pk_add_f32 v[8:9], v[8:9], v[40:41]
	v_pk_add_f32 v[10:11], v[10:11], v[42:43]
	v_pk_add_f32 v[4:5], v[4:5], v[36:37]
	v_pk_add_f32 v[6:7], v[6:7], v[38:39]
	global_store_dwordx4 v182, v[8:11], s[86:87] offset:512
	global_store_dwordx4 v183, v[4:7], s[86:87] offset:512
	v_fmac_f32_e32 v191, v8, v8
	v_fmac_f32_e32 v191, v9, v9
	v_fmac_f32_e32 v191, v10, v10
	v_fmac_f32_e32 v191, v11, v11
	v_fmac_f32_e32 v192, v4, v4
	v_fmac_f32_e32 v192, v5, v5
	v_fmac_f32_e32 v192, v6, v6
	v_fmac_f32_e32 v192, v7, v7
	v_pk_mul_f32 v[224:225], v[8:9], v[152:153]
	v_pk_mul_f32 v[226:227], v[10:11], v[154:155]
	v_cvt_pk_bf16_f32 v210, v224, v225
	v_cvt_pk_bf16_f32 v211, v226, v227
	global_store_dwordx2 v184, v[210:211], s[88:89] offset:256
	v_pk_mul_f32 v[224:225], v[4:5], v[160:161]
	v_pk_mul_f32 v[226:227], v[6:7], v[162:163]
	v_cvt_pk_bf16_f32 v212, v224, v225
	v_cvt_pk_bf16_f32 v213, v226, v227
	global_store_dwordx2 v185, v[212:213], s[88:89] offset:256
	s_nop 1
	v_add_f32_dpp v193, v191, v191 row_ror:8 row_mask:0xf bank_mask:0xf
	v_add_f32_dpp v181, v192, v192 row_ror:8 row_mask:0xf bank_mask:0xf
	v_cndmask_b32_e64 v191, v193, v181, s[90:91]
	ds_bpermute_b32 v192, v189, v191
	s_waitcnt lgkmcnt(0)
	v_add_f32_e32 v191, v191, v192
	ds_bpermute_b32 v192, v190, v191
	s_waitcnt lgkmcnt(0)
	v_add_f32_e32 v191, v191, v192
	s_and_saveexec_b64 s[14:15], s[40:41]
	global_store_dword v188, v191, s[92:93]
	s_or_b64 exec, exec, s[14:15]
	v_readlane_b32 s68, v254, 45
	v_readlane_b32 s69, v254, 48
	v_mov_b32_e32 v232, 0x6c0
	v_mov_b32_e32 v233, 0x750
	v_mov_b32_e32 v234, 0x7e0
	v_mov_b32_e32 v235, 0x870
